# post_odd loop: gn loads hoisted, 3 gate loads issued at trip top, then all 9 loads software-pipelined one trip ahead
# speedup vs baseline: 1.0096x; 1.0001x over previous
; __device__ __forceinline__ int BIDX() { int t = blockIdx.x; asm volatile("" : "+s"(t)); return t; }
; __device__ __forceinline__ const float* INP(const Params& p, int k) { return p.in[k] + opaque0(); }
; __device__ __forceinline__ char* WS(const Params& p) { return p.ws + opaque0(); }
; __device__ __forceinline__ uint2 ld_nt8(const void* p) { const u32x2_t t = __builtin_nontemporal_load((const u32x2_t*)p); return make_uint2(t[0], t[1]); }
; __device__ __forceinline__ float lo_bf(unsigned u) { return __uint_as_float(u << 16); }
; __device__ __forceinline__ float hi_bf(unsigned u) { return __uint_as_float(u & 0xffff0000u); }
; __device__ void post_odd_phase(int swave, const Params& p, int j) {
;   const int tidx = TIDX(swave);
;   const int bidx = BIDX();
;   const bf16_t* P = (const bf16_t*)(WS(p) + OFF_PU);
;   const bf16_t* OF = (const bf16_t*)(WS(p) + OFF_OFB);
;   const bf16_t* OB = (const bf16_t*)(WS(p) + OFF_OFB + OFB_OB_ODD);
;   bf16_t* Y = (bf16_t*)(WS(p) + OFF_A16);
;   const float* gn = INP(p, 13) + (size_t)j * 768;
;   const int l16 = tidx & 15;
;   for (int it = bidx * 32 + (tidx >> 4); it < TOK * 4; it += gridDim.x * 32) {
;     const int h = it & 3, token = it >> 2;
;     float o[12]; float sm = 0.f;
; #pragma unroll
;     for (int e = 0; e < 3; ++e) {
;       const size_t oidx = (size_t)token * 768 + h * 192 + e * 64 + l16 * 4;
;       const uint2 a = ld_nt8(OF + oidx), bq = ld_nt8(OB + oidx);
;       o[4 * e] = lo_bf(a.x) + lo_bf(bq.x); o[4 * e + 1] = hi_bf(a.x) + hi_bf(bq.x); o[4 * e + 2] = lo_bf(a.y) + lo_bf(bq.y); o[4 * e + 3] = hi_bf(a.y) + hi_bf(bq.y);
;       sm += o[4 * e] + o[4 * e + 1] + o[4 * e + 2] + o[4 * e + 3];
;     }
;     const float mu = row16_allsum(sm) * (1.f / 192.f);
;     float vs = 0.f;
; #pragma unroll
;     for (int e = 0; e < 12; ++e) { o[e] -= mu; vs += o[e] * o[e]; }
;     const float rs = rsqrtf(row16_allsum(vs) * (1.f / 192.f) + EPS);
; #pragma unroll
;     for (int e = 0; e < 3; ++e) {
;       const int c = h * 192 + e * 64 + l16 * 4;
;       const uint2 gt = ld_nt8(P + (size_t)token * ODD_IN + O_RG + c);
.LBB0_60:
	s_and_b64 vcc, exec, s[2:3]
	v_writelane_b32 v247, s13, 63
	s_cbranch_vccz .LBB0_703
	v_readlane_b32 s0, v247, 63
	s_cmp_gt_i32 s0, 1
	s_mov_b64 s[0:1], -1
	s_cbranch_scc0 .LBB0_701
	v_readlane_b32 s0, v247, 63
	s_cmp_gt_i32 s0, 2
	s_mov_b64 s[0:1], -1
	s_cbranch_scc0 .LBB0_74
	v_readlane_b32 s2, v247, 53
	v_readlane_b32 s3, v247, 54
	s_and_b64 vcc, exec, s[2:3]
	s_cbranch_vccz .LBB0_68
	v_mov_b32_e32 v0, v147
	s_mov_b32 s0, s85
	s_mov_b64 s[4:5], 0
	v_ashrrev_i32_e32 v1, 4, v0
	v_lshl_add_u32 v40, s0, 5, v1
	s_mov_b32 s0, 0x20000
	s_mov_b64 s[6:7], 0
	s_mov_b64 s[8:9], 0
	s_mov_b64 s[10:11], 0
	s_mov_b64 s[2:3], 0
	v_cmp_gt_i32_e32 vcc, s0, v40
	s_and_saveexec_b64 s[0:1], vcc
	v_readlane_b32 s16, v247, 0
	s_cbranch_execz .LBB0_67
	v_readlane_b32 s12, v248, 8
	v_readlane_b32 s14, v248, 10
	v_readlane_b32 s15, v248, 11
	s_add_u32 s4, s14, s4
	s_addc_u32 s5, s15, s5
	s_add_u32 s6, s14, s6
	s_addc_u32 s7, s15, s7
	s_add_u32 s6, s6, 0x4000000
	s_addc_u32 s7, s7, 0
	s_add_u32 s8, s14, s8
	s_addc_u32 s9, s15, s9
	s_add_u32 s8, s8, 0x7000000
	s_addc_u32 s9, s9, 0
	v_readlane_b32 s13, v248, 9
	s_add_u32 s10, s14, s10
	v_readlane_b32 s68, v248, 28
	s_addc_u32 s11, s15, s11
	s_lshl_b64 s[2:3], s[2:3], 2
	v_readlane_b32 s78, v248, 38
	v_readlane_b32 s12, v247, 47
	v_readlane_b32 s79, v248, 39
	s_add_u32 s2, s78, s2
	v_readlane_b32 s13, v247, 48
	s_mov_b32 s14, s12
	v_lshlrev_b32_e32 v1, 2, v0
	v_bfe_u32 v0, v0, 4, 2
	s_addc_u32 s3, s79, s3
	s_mul_i32 s13, s14, 0xc00
	v_mul_u32_u24_e32 v0, 0xc0, v0
	s_mul_hi_i32 s12, s12, 0xc00
	s_add_u32 s2, s2, s13
	v_and_or_b32 v0, v1, 60, v0
	s_addc_u32 s3, s3, s12
	v_lshlrev_b32_e32 v2, 2, v0
	s_waitcnt vmcnt(0)
	v_lshl_add_u64 v[8:9], s[2:3], 0, v[2:3]
	v_lshlrev_b32_e32 v2, 1, v0
	v_mov_b32_e32 v1, v3
	v_lshl_add_u64 v[10:11], s[10:11], 0, v[2:3]
	s_mov_b64 s[10:11], 0
	v_readlane_b32 s69, v248, 29
	v_readlane_b32 s70, v248, 30
	v_readlane_b32 s71, v248, 31
	v_readlane_b32 s72, v248, 32
	v_readlane_b32 s73, v248, 33
	v_readlane_b32 s74, v248, 34
	v_readlane_b32 s75, v248, 35
	v_readlane_b32 s76, v248, 36
	v_readlane_b32 s77, v248, 37
	v_readlane_b32 s80, v248, 40
	v_readlane_b32 s81, v248, 41
	v_readlane_b32 s82, v248, 42
	v_readlane_b32 s83, v248, 43
	global_load_dwordx4 v[60:63], v[8:9], off
	global_load_dwordx4 v[64:67], v[8:9], off offset:256
	global_load_dwordx4 v[68:71], v[8:9], off offset:512
	v_ashrrev_i32_e32 v4, 2, v40
	v_mad_i64_i32 v[6:7], s[2:3], v4, s52, v[0:1]
	v_lshlrev_b64 v[6:7], 1, v[6:7]
	v_lshl_add_u64 v[12:13], s[6:7], 0, v[6:7]
	global_load_dwordx2 v[76:77], v[12:13], off nt
	v_lshl_add_u64 v[6:7], s[8:9], 0, v[6:7]
	global_load_dwordx2 v[78:79], v[6:7], off nt
	global_load_dwordx2 v[80:81], v[12:13], off offset:128 nt
	global_load_dwordx2 v[82:83], v[6:7], off offset:128 nt
	global_load_dwordx2 v[84:85], v[12:13], off offset:256 nt
	global_load_dwordx2 v[86:87], v[6:7], off offset:256 nt
	v_mov_b64_e32 v[6:7], s[4:5]
	v_mad_i64_i32 v[6:7], s[2:3], v4, s55, v[6:7]
	v_lshlrev_b32_e32 v2, 1, v0
	v_lshl_add_u64 v[4:5], v[6:7], 0, v[2:3]
	s_mov_b64 s[2:3], 0xc000e00
	v_lshl_add_u64 v[12:13], v[4:5], 0, s[2:3]
	global_load_dwordx2 v[88:89], v[12:13], off nt
	global_load_dwordx2 v[90:91], v[12:13], off offset:128 nt
	global_load_dwordx2 v[92:93], v[12:13], off offset:256 nt
	s_waitcnt vmcnt(0)
.LBB0_66:
	v_ashrrev_i32_e32 v4, 2, v40
	v_ashrrev_i32_e32 v5, 31, v4
	v_lshlrev_b64 v[16:17], 11, v[4:5]
	v_lshl_add_u64 v[16:17], v[10:11], 0, v[16:17]
	v_mov_b32_e32 v14, v76
	v_mov_b32_e32 v15, v77
	v_mov_b32_e32 v28, v78
	v_mov_b32_e32 v29, v79
	v_mov_b32_e32 v34, v80
	v_mov_b32_e32 v35, v81
	v_mov_b32_e32 v36, v82
	v_mov_b32_e32 v37, v83
	v_mov_b32_e32 v38, v84
	v_mov_b32_e32 v39, v85
	v_mov_b32_e32 v42, v86
	v_mov_b32_e32 v43, v87
	v_mov_b32_e32 v44, v88
	v_mov_b32_e32 v45, v89
	v_mov_b32_e32 v72, v90
	v_mov_b32_e32 v73, v91
	v_mov_b32_e32 v74, v92
	v_mov_b32_e32 v75, v93
	v_mov_b32_e32 v26, v3
	v_add_u32_e32 v40, s16, v40
	v_cmp_ge_i32_e32 vcc, s64, v40
	s_and_saveexec_b64 s[12:13], vcc
	s_cbranch_execz .Lpo_nopf
	v_ashrrev_i32_e32 v4, 2, v40
	v_mad_i64_i32 v[6:7], s[2:3], v4, s52, v[0:1]
	v_lshlrev_b64 v[6:7], 1, v[6:7]
	v_lshl_add_u64 v[12:13], s[6:7], 0, v[6:7]
	global_load_dwordx2 v[76:77], v[12:13], off nt
	v_lshl_add_u64 v[6:7], s[8:9], 0, v[6:7]
	global_load_dwordx2 v[78:79], v[6:7], off nt
	global_load_dwordx2 v[80:81], v[12:13], off offset:128 nt
	global_load_dwordx2 v[82:83], v[6:7], off offset:128 nt
	global_load_dwordx2 v[84:85], v[12:13], off offset:256 nt
	global_load_dwordx2 v[86:87], v[6:7], off offset:256 nt
	v_mov_b64_e32 v[6:7], s[4:5]
	v_mad_i64_i32 v[6:7], s[2:3], v4, s55, v[6:7]
	v_lshlrev_b32_e32 v2, 1, v0
	v_lshl_add_u64 v[4:5], v[6:7], 0, v[2:3]
	s_mov_b64 s[2:3], 0xc000e00
	v_lshl_add_u64 v[12:13], v[4:5], 0, s[2:3]
	global_load_dwordx2 v[88:89], v[12:13], off nt
	global_load_dwordx2 v[90:91], v[12:13], off offset:128 nt
	global_load_dwordx2 v[92:93], v[12:13], off offset:256 nt
; __device__ __forceinline__ uint2 ld_nt8(const void* p) { const u32x2_t t = __builtin_nontemporal_load((const u32x2_t*)p); return make_uint2(t[0], t[1]); }
; __device__ __forceinline__ unsigned pk2(float lo, float hi) { f32x2_t v = {lo, hi}; bf16x2_t b = __builtin_convertvector(v, bf16x2_t); return __builtin_bit_cast(unsigned, b); }
; __device__ __forceinline__ float lo_bf(unsigned u) { return __uint_as_float(u << 16); }
; __device__ __forceinline__ float hi_bf(unsigned u) { return __uint_as_float(u & 0xffff0000u); }
; __device__ __forceinline__ float siluf_(float x) { return x * __builtin_amdgcn_rcpf(1.f + __expf(-x)); }
; __device__ void post_odd_phase(int swave, const Params& p, int j) {
;     ...
;     const int h = it & 3, token = it >> 2;
;     float o[12]; float sm = 0.f;
; #pragma unroll
;     for (int e = 0; e < 3; ++e) {
;       const size_t oidx = (size_t)token * 768 + h * 192 + e * 64 + l16 * 4;
;       const uint2 a = ld_nt8(OF + oidx), bq = ld_nt8(OB + oidx);
;       o[4 * e] = lo_bf(a.x) + lo_bf(bq.x); o[4 * e + 1] = hi_bf(a.x) + hi_bf(bq.x); o[4 * e + 2] = lo_bf(a.y) + lo_bf(bq.y); o[4 * e + 3] = hi_bf(a.y) + hi_bf(bq.y);
;       sm += o[4 * e] + o[4 * e + 1] + o[4 * e + 2] + o[4 * e + 3];
;     }
;     const float mu = row16_allsum(sm) * (1.f / 192.f);
;     float vs = 0.f;
; #pragma unroll
;     for (int e = 0; e < 12; ++e) { o[e] -= mu; vs += o[e] * o[e]; }
;     const float rs = rsqrtf(row16_allsum(vs) * (1.f / 192.f) + EPS);
; #pragma unroll
;     for (int e = 0; e < 3; ++e) {
;       const int c = h * 192 + e * 64 + l16 * 4;
;       const uint2 gt = ld_nt8(P + (size_t)token * ODD_IN + O_RG + c);
;       const float4 g4 = *(const float4*)(gn + c);
;       uint2 ov;
;       ov.x = pk2(o[4 * e] * rs * g4.x * siluf_(lo_bf(gt.x)), o[4 * e + 1] * rs * g4.y * siluf_(hi_bf(gt.x)));
;       ov.y = pk2(o[4 * e + 2] * rs * g4.z * siluf_(lo_bf(gt.y)), o[4 * e + 3] * rs * g4.w * siluf_(hi_bf(gt.y)));
;       *(uint2*)(Y + (size_t)token * DM + c) = ov;
;     }
.Lpo_nopf:
	s_or_b64 exec, exec, s[12:13]
	v_lshlrev_b32_e32 v6, 16, v29
	v_lshlrev_b32_e32 v4, 16, v15
	v_and_b32_e32 v5, 0xffff0000, v15
	v_and_b32_e32 v7, 0xffff0000, v29
	v_pk_add_f32 v[30:31], v[4:5], v[6:7]
	v_lshlrev_b32_e32 v32, 16, v14
	v_and_b32_e32 v33, 0xffff0000, v14
	v_lshlrev_b32_e32 v14, 16, v28
	v_and_b32_e32 v15, 0xffff0000, v28
	v_pk_add_f32 v[32:33], v[32:33], v[14:15]
	v_lshlrev_b32_e32 v22, 16, v36
	v_pk_add_f32 v[28:29], v[32:33], v[32:33] op_sel:[0,1] op_sel_hi:[1,0]
	v_lshlrev_b32_e32 v24, 16, v34
	v_and_b32_e32 v23, 0xffff0000, v36
	v_and_b32_e32 v25, 0xffff0000, v34
	v_lshlrev_b32_e32 v48, 16, v37
	v_and_b32_e32 v34, 0xffff0000, v35
	v_and_b32_e32 v36, 0xffff0000, v37
	v_lshlrev_b32_e32 v14, 16, v44
	v_mul_f32_e32 v2, 0xbfb8aa3b, v14
	v_exp_f32_e32 v2, v2
	v_and_b32_e32 v15, 0xffff0000, v44
	v_lshlrev_b32_e32 v37, 16, v43
	v_and_b32_e32 v18, 0xffff0000, v39
	v_add_f32_e32 v2, 1.0, v2
	v_rcp_f32_e32 v46, v2
	v_mul_f32_e32 v2, 0xbfb8aa3b, v15
	v_exp_f32_e32 v2, v2
	v_and_b32_e32 v27, 0xffff0000, v43
	v_and_b32_e32 v19, 0xffff0000, v38
	v_and_b32_e32 v21, 0xffff0000, v42
	v_add_f32_e32 v2, 1.0, v2
	v_rcp_f32_e32 v47, v2
	v_lshlrev_b32_e32 v49, 16, v42
	v_pk_add_f32 v[22:23], v[24:25], v[22:23]
	v_pk_mul_f32 v[14:15], v[46:47], v[14:15]
	v_pk_add_f32 v[46:47], v[30:31], v[28:29]
	v_lshlrev_b32_e32 v28, 16, v35
	v_lshlrev_b32_e32 v35, 16, v39
	v_pk_add_f32 v[34:35], v[34:35], v[36:37]
	v_pk_add_f32 v[36:37], v[30:31], v[46:47] op_sel:[1,0] op_sel_hi:[0,1]
	v_mov_b32_e32 v37, v18
	v_lshlrev_b32_e32 v29, 16, v38
	v_pk_add_f32 v[38:39], v[36:37], v[26:27]
	v_lshlrev_b32_e32 v26, 16, v45
	v_mul_f32_e32 v2, 0xbfb8aa3b, v26
	v_exp_f32_e32 v2, v2
	v_and_b32_e32 v27, 0xffff0000, v45
	v_mov_b32_e32 v18, v22
	v_mov_b32_e32 v20, v23
	v_add_f32_e32 v2, 1.0, v2
	v_rcp_f32_e32 v42, v2
	v_mul_f32_e32 v2, 0xbfb8aa3b, v27
	v_exp_f32_e32 v2, v2
	v_pk_add_f32 v[28:29], v[28:29], v[48:49]
	v_pk_add_f32 v[24:25], v[18:19], v[20:21]
	v_mov_b32_e32 v36, v39
	v_pk_add_f32 v[18:19], v[28:29], v[24:25]
	v_add_f32_e32 v2, 1.0, v2
	v_pk_add_f32 v[18:19], v[34:35], v[18:19]
	v_rcp_f32_e32 v43, v2
	v_pk_add_f32 v[18:19], v[38:39], v[18:19]
	v_mov_b32_e32 v37, v35
	v_add_f32_e32 v2, v18, v19
	v_pk_mul_f32 v[26:27], v[42:43], v[26:27]
	v_mov_b32_e32 v42, v28
	v_add_f32_dpp v2, v2, v2 row_ror:8 row_mask:0xf bank_mask:0xf bound_ctrl:1
	v_mov_b32_e32 v43, v34
	v_mov_b32_e32 v24, v29
	v_add_f32_dpp v2, v2, v2 row_ror:4 row_mask:0xf bank_mask:0xf bound_ctrl:1
	s_nop 1
	v_add_f32_dpp v2, v2, v2 row_ror:2 row_mask:0xf bank_mask:0xf bound_ctrl:1
	s_nop 1
	v_add_f32_dpp v2, v2, v2 row_ror:1 row_mask:0xf bank_mask:0xf bound_ctrl:1
	v_mul_f32_e32 v2, 0x3baaaaab, v2
	v_pk_add_f32 v[32:33], v[32:33], v[2:3] op_sel_hi:[1,0] neg_lo:[0,1] neg_hi:[0,1]
	v_pk_add_f32 v[30:31], v[30:31], v[2:3] op_sel_hi:[1,0] neg_lo:[0,1] neg_hi:[0,1]
	v_pk_mul_f32 v[34:35], v[32:33], v[32:33]
	v_pk_mul_f32 v[38:39], v[30:31], v[30:31]
	v_pk_add_f32 v[22:23], v[22:23], v[2:3] op_sel_hi:[1,0] neg_lo:[0,1] neg_hi:[0,1]
	v_pk_add_f32 v[18:19], v[36:37], v[2:3] op_sel_hi:[1,0] neg_lo:[0,1] neg_hi:[0,1]
	v_pk_add_f32 v[20:21], v[42:43], v[2:3] op_sel_hi:[1,0] neg_lo:[0,1] neg_hi:[0,1]
	v_pk_add_f32 v[24:25], v[24:25], v[2:3] op_sel_hi:[1,0] neg_lo:[0,1] neg_hi:[0,1]
	v_add_f32_e32 v2, v34, v35
	v_add_f32_e32 v2, v38, v2
	v_pk_mul_f32 v[44:45], v[22:23], v[22:23]
	v_add_f32_e32 v2, v39, v2
	v_add_f32_e32 v2, v44, v2
	v_pk_mul_f32 v[42:43], v[20:21], v[20:21]
	v_add_f32_e32 v2, v45, v2
	v_add_f32_e32 v2, v42, v2
	v_pk_mul_f32 v[28:29], v[24:25], v[24:25]
	v_add_f32_e32 v2, v43, v2
	v_add_f32_e32 v2, v28, v2
	v_pk_mul_f32 v[36:37], v[18:19], v[18:19]
	v_add_f32_e32 v2, v29, v2
	v_add_f32_e32 v2, v37, v2
	v_add_f32_e32 v2, v36, v2
	s_nop 1
	v_add_f32_dpp v2, v2, v2 row_ror:8 row_mask:0xf bank_mask:0xf bound_ctrl:1
	s_nop 1
	v_add_f32_dpp v2, v2, v2 row_ror:4 row_mask:0xf bank_mask:0xf bound_ctrl:1
	s_nop 1
	v_add_f32_dpp v2, v2, v2 row_ror:2 row_mask:0xf bank_mask:0xf bound_ctrl:1
	s_nop 1
	v_add_f32_dpp v2, v2, v2 row_ror:1 row_mask:0xf bank_mask:0xf bound_ctrl:1
	v_fmamk_f32 v2, v2, 0x3baaaaab, v132
	v_cmp_gt_f32_e32 vcc, s26, v2
	v_mul_f32_e32 v28, 0x4b800000, v2
	s_nop 0
	v_cndmask_b32_e32 v2, v2, v28, vcc
	v_rsq_f32_e32 v2, v2
	s_nop 0
	v_mul_f32_e32 v28, 0x45800000, v2
	v_cndmask_b32_e32 v2, v2, v28, vcc
	v_pk_mul_f32 v[28:29], v[32:33], v[2:3] op_sel_hi:[1,0]
	v_pk_mul_f32 v[22:23], v[22:23], v[2:3] op_sel_hi:[1,0]
	v_pk_mul_f32 v[4:5], v[60:61], v[28:29]
	v_pk_mul_f32 v[20:21], v[20:21], v[2:3] op_sel_hi:[1,0]
	v_pk_mul_f32 v[4:5], v[14:15], v[4:5]
	v_pk_mul_f32 v[14:15], v[30:31], v[2:3] op_sel_hi:[1,0]
	v_cvt_pk_bf16_f32 v4, v4, v5
	v_pk_mul_f32 v[6:7], v[62:63], v[14:15]
	v_pk_mul_f32 v[18:19], v[18:19], v[2:3] op_sel_hi:[1,0]
	v_pk_mul_f32 v[6:7], v[26:27], v[6:7]
	v_cmp_lt_i32_e32 vcc, s64, v40
	v_cvt_pk_bf16_f32 v5, v6, v7
	global_store_dwordx2 v[16:17], v[4:5], off
	s_nop 0
	s_or_b64 s[10:11], vcc, s[10:11]
	v_lshlrev_b32_e32 v26, 16, v72
	v_and_b32_e32 v27, 0xffff0000, v72
	v_mul_f32_e32 v14, 0xbfb8aa3b, v26
	v_exp_f32_e32 v14, v14
	v_pk_mul_f32 v[4:5], v[64:65], v[22:23]
	v_pk_mul_f32 v[6:7], v[66:67], v[20:21]
	v_add_f32_e32 v14, 1.0, v14
	v_rcp_f32_e32 v28, v14
	v_mul_f32_e32 v14, 0xbfb8aa3b, v27
	v_exp_f32_e32 v14, v14
	s_nop 0
	v_add_f32_e32 v14, 1.0, v14
	v_rcp_f32_e32 v29, v14
	v_lshlrev_b32_e32 v14, 16, v73
	v_and_b32_e32 v15, 0xffff0000, v73
	v_pk_mul_f32 v[22:23], v[28:29], v[26:27]
	s_nop 0
	v_pk_mul_f32 v[4:5], v[22:23], v[4:5]
	s_nop 0
	v_cvt_pk_bf16_f32 v4, v4, v5
	v_mul_f32_e32 v5, 0xbfb8aa3b, v14
	v_exp_f32_e32 v5, v5
	s_nop 0
	v_add_f32_e32 v5, 1.0, v5
	v_rcp_f32_e32 v22, v5
	v_mul_f32_e32 v5, 0xbfb8aa3b, v15
	v_exp_f32_e32 v5, v5
	s_nop 0
	v_add_f32_e32 v5, 1.0, v5
	v_rcp_f32_e32 v23, v5
	s_nop 0
	v_pk_mul_f32 v[14:15], v[22:23], v[14:15]
	s_nop 0
	v_pk_mul_f32 v[6:7], v[14:15], v[6:7]
	v_pk_mul_f32 v[22:23], v[24:25], v[2:3] op_sel_hi:[1,0]
	v_cvt_pk_bf16_f32 v5, v6, v7
	global_store_dwordx2 v[16:17], v[4:5], off offset:128
	s_nop 0
	v_lshlrev_b32_e32 v14, 16, v74
	v_and_b32_e32 v15, 0xffff0000, v74
	v_mul_f32_e32 v12, 0xbfb8aa3b, v14
	v_exp_f32_e32 v12, v12
	v_pk_mul_f32 v[4:5], v[68:69], v[22:23]
	v_pk_mul_f32 v[6:7], v[70:71], v[18:19] op_sel:[0,1] op_sel_hi:[1,0]
	v_add_f32_e32 v12, 1.0, v12
	v_rcp_f32_e32 v20, v12
	v_mul_f32_e32 v12, 0xbfb8aa3b, v15
	v_exp_f32_e32 v12, v12
	s_nop 0
	v_add_f32_e32 v12, 1.0, v12
	v_rcp_f32_e32 v21, v12
	v_lshlrev_b32_e32 v12, 16, v75
	v_and_b32_e32 v13, 0xffff0000, v75
	v_mul_f32_e32 v2, 0xbfb8aa3b, v13
	v_pk_mul_f32 v[14:15], v[20:21], v[14:15]
	v_exp_f32_e32 v2, v2
	v_pk_mul_f32 v[4:5], v[14:15], v[4:5]
	v_add_f32_e32 v2, 1.0, v2
	v_cvt_pk_bf16_f32 v4, v4, v5
	v_mul_f32_e32 v5, 0xbfb8aa3b, v12
	v_exp_f32_e32 v5, v5
	v_rcp_f32_e32 v15, v2
	v_add_f32_e32 v5, 1.0, v5
	v_rcp_f32_e32 v14, v5
	s_nop 0
	v_pk_mul_f32 v[12:13], v[14:15], v[12:13]
	s_nop 0
	v_pk_mul_f32 v[6:7], v[12:13], v[6:7]
	s_nop 0
	v_cvt_pk_bf16_f32 v5, v6, v7
	global_store_dwordx2 v[16:17], v[4:5], off offset:256
	s_waitcnt vmcnt(3)
; __device__ void post_odd_phase(int swave, const Params& p, int j) {
;     ...
;   for (int it = bidx * 32 + (tidx >> 4); it < TOK * 4; it += gridDim.x * 32) {
	s_andn2_b64 exec, exec, s[10:11]
	s_cbranch_execnz .LBB0_66
